# also the neighbourhood loop head and the GQA tail loop head on 256-byte boundaries
# baseline (speedup 1.0000x reference)
.LBB0_721:
	v_mad_i64_i32 v[194:195], s[0:1], s20, v217, v[194:195]
	s_add_i32 s20, s8, 0x40c0
	s_movk_i32 s21, 0x7f
	s_movk_i32 s22, 0x4000
	s_movk_i32 s23, 0x2000
	s_mov_b32 s0, 0
	.p2alignl 8, 3212836864

.LBB0_769:
	s_or_b64 exec, exec, s[2:3]
	s_ashr_i32 s1, s0, 31
	s_lshl_b64 s[2:3], s[0:1], 13
	s_lshl_b32 s1, s6, 8
	s_or_b32 s2, s2, s1
	s_sub_i32 s8, s7, s19
	s_mul_hi_u32 s7, s2, 0xe00
	s_mul_i32 s9, s3, 0xe00
	s_mul_i32 s6, s2, 0xe00
	s_add_i32 s7, s7, s9
	v_readlane_b32 s10, v254, 35
	v_readlane_b32 s11, v254, 36
	s_add_u32 s9, s10, s6
	s_addc_u32 s10, s11, s7
	s_lshl_b32 s6, s5, 6
	s_ashr_i32 s7, s6, 31
	s_lshl_b64 s[36:37], s[6:7], 1
	s_add_u32 s11, s9, s36
	s_addc_u32 s18, s10, s37
	s_add_u32 s6, s12, s36
	s_addc_u32 s7, s13, s37
	s_add_u32 s22, s14, s36
	s_addc_u32 s23, s15, s37
	s_lshl_b32 s9, s0, 8
	s_lshl_b32 s0, s0, 13
	s_lshl_b32 s5, s19, 6
	s_add_i32 s26, s9, 0x4000
	s_or_b32 s10, s5, s0
	v_mov_b32_e32 v14, v191
	s_cmp_eq_u32 s8, 1
	s_waitcnt lgkmcnt(0)
	s_barrier
	s_cselect_b32 s20, 12, 16
	v_readfirstlane_b32 s5, v14
	s_ashr_i32 s17, s5, 6
	v_and_b32_e32 v178, 63, v14
	s_lshl_b32 s44, s17, 5
	s_ashr_i32 s45, s44, 31
	s_mul_i32 s8, s17, 0x1c000
	v_mul_u32_u24_e32 v0, 0x700, v178
	s_mul_hi_i32 s21, s44, 0xe00
	s_add_u32 s24, s11, s8
	v_lshlrev_b32_e32 v0, 1, v0
	s_addc_u32 s25, s18, s21
	v_lshl_add_u64 v[2:3], s[6:7], 0, v[0:1]
	s_lshl_b32 s6, s17, 3
	s_ashr_i32 s7, s6, 31
	v_lshl_add_u64 v[174:175], s[6:7], 1, v[2:3]
	s_lshl_b32 s6, s17, 4
	v_bfe_u32 v0, v14, 2, 4
	v_and_or_b32 v0, s6, 48, v0
	s_ashr_i32 s6, s5, 3
	v_mul_u32_u24_e32 v0, 0x700, v0
	s_andn2_b32 s6, s6, 31
	s_and_b32 s11, s5, 0x3fffffc0
	v_lshlrev_b32_e32 v0, 1, v0
	s_ashr_i32 s7, s6, 31
	v_lshlrev_b32_e32 v179, 3, v14
	s_lshl_b32 s21, s17, 10
	v_lshl_add_u64 v[2:3], s[22:23], 0, v[0:1]
	v_and_b32_e32 v189, 24, v179
	s_cmp_lg_u32 0, -1
	v_lshl_add_u64 v[2:3], s[6:7], 1, v[2:3]
	v_lshlrev_b32_e32 v0, 1, v189
	s_cselect_b32 s6, 0, 0
	v_lshl_add_u64 v[176:177], v[2:3], 0, v[0:1]
	s_add_i32 s21, s21, s6
	v_mad_i64_i32 v[2:3], s[6:7], s26, v217, v[174:175]
	v_and_b32_e32 v180, 31, v14
	v_bfe_u32 v181, v14, 5, 1
	s_mov_b32 m0, s21
	s_nop 0
	global_load_lds_dwordx4 v[2:3], off
	s_add_i32 s22, s21, 0x6000
	v_mad_i64_i32 v[2:3], s[6:7], s26, v217, v[176:177]
	s_mov_b32 m0, s22
	s_nop 0
	global_load_lds_dwordx4 v[2:3], off
	s_add_i32 s7, s9, 0x4040
	v_mul_u32_u24_e32 v0, 0x700, v180
	v_lshlrev_b32_e32 v193, 4, v181
	v_mad_i64_i32 v[2:3], s[26:27], s7, v217, v[174:175]
	s_add_i32 s6, s21, 0x2000
	s_mov_b32 m0, s6
	s_nop 0
	global_load_lds_dwordx4 v[2:3], off
	v_lshl_or_b32 v0, v0, 1, v193
	global_load_dwordx4 v[126:129], v0, s[24:25] offset:1280
	global_load_dwordx4 v[118:121], v0, s[24:25] offset:1312
	global_load_dwordx4 v[106:109], v0, s[24:25] offset:1344
	global_load_dwordx4 v[98:101], v0, s[24:25] offset:1376
	v_lshlrev_b32_e32 v0, 10, v181
	v_lshlrev_b32_e32 v2, 4, v180
	s_add_i32 s8, s9, 0x4080
	v_add3_u32 v197, 0, v0, v2
	v_mad_i64_i32 v[2:3], s[24:25], s8, v217, v[174:175]
	s_add_i32 s6, s21, 0x4000
	s_mov_b32 m0, s6
	s_nop 0
	global_load_lds_dwordx4 v[2:3], off
	s_waitcnt vmcnt(3) lgkmcnt(0)
	s_barrier
	ds_read_b128 v[2:5], v197
	ds_read_b128 v[6:9], v197 offset:512
	s_addk_i32 s9, 0x40c0
	s_lshl_b32 s11, s11, 2
	s_add_i32 s18, s11, 0
	v_lshlrev_b32_e32 v0, 1, v14
	s_mov_b32 s56, 0
	v_and_b32_e32 v192, 32, v0
	s_mov_b32 s57, s56
	v_add_u32_e32 v54, 0, v192
	s_ashr_i32 s5, s5, 7
	s_mov_b32 s58, s56
	s_mov_b32 s59, s56
	s_mov_b32 s60, s56
	s_mov_b32 s61, s56
	s_mov_b32 s62, s56
	s_waitcnt vmcnt(3) lgkmcnt(1)
	v_mfma_f32_32x32x16_bf16 v[34:49], v[2:5], v[126:129], 0
	s_mov_b32 s63, s56
	s_mov_b32 s64, s56
	s_mov_b32 s65, s56
	s_mov_b32 s66, s56
	s_mov_b32 s67, s56
	s_mov_b32 s68, s56
	s_mov_b32 s69, s56
	s_waitcnt lgkmcnt(0)
	v_mfma_f32_32x32x16_bf16 v[18:33], v[6:9], v[126:129], 0
	ds_read_b128 v[2:5], v197 offset:2048
	ds_read_b128 v[6:9], v197 offset:2560
	s_mov_b32 s70, s56
	s_mov_b32 s71, s56
	s_or_b32 s0, s0, s1
	s_mov_b32 s23, 1
	s_movk_i32 s6, 0x4000
	s_mov_b32 s38, -1
	s_waitcnt vmcnt(2) lgkmcnt(1)
	v_mfma_f32_32x32x16_bf16 v[34:49], v[2:5], v[118:121], v[34:49]
	ds_read_b128 v[2:5], v197 offset:4608
	ds_read_b128 v[10:13], v197 offset:4096
	s_movk_i32 s35, 0x2000
	v_and_or_b32 v198, s44, 32, v180
	v_cmp_gt_u32_e64 s[40:41], 32, v178
	v_lshl_add_u32 v194, v180, 2, s18
	v_mov_b32_e32 v200, 0
	s_mov_b32 s33, 64
	s_waitcnt lgkmcnt(2)
	v_mfma_f32_32x32x16_bf16 v[18:33], v[6:9], v[118:121], v[18:33]
	ds_read_b128 v[50:53], v197 offset:6656
	ds_read_b128 v[6:9], v197 offset:6144
	s_waitcnt vmcnt(1) lgkmcnt(2)
	v_mfma_f32_32x32x16_bf16 v[34:49], v[10:13], v[106:109], v[34:49]
	v_mfma_f32_32x32x16_bf16 v[18:33], v[2:5], v[106:109], v[18:33]
	v_lshlrev_b32_e32 v2, 4, v14
	v_and_b32_e32 v0, 0xc0, v2
	v_lshl_or_b32 v0, v181, 8, v0
	v_add3_u32 v195, v54, v189, v0
	s_waitcnt vmcnt(0) lgkmcnt(0)
	v_mfma_f32_32x32x16_bf16 v[34:49], v[6:9], v[98:101], v[34:49]
	v_mov_b64_e32 v[2:3], s[56:57]
	v_mov_b64_e32 v[16:17], s[70:71]
	v_mov_b64_e32 v[4:5], s[58:59]
	v_mov_b64_e32 v[6:7], s[60:61]
	v_mov_b64_e32 v[8:9], s[62:63]
	v_mov_b64_e32 v[10:11], s[64:65]
	v_mov_b64_e32 v[12:13], s[66:67]
	v_mfma_f32_32x32x16_bf16 v[18:33], v[50:53], v[98:101], v[18:33]
	s_nop 15
	s_nop 7
	s_waitcnt vmcnt(0) lgkmcnt(0)
	s_barrier
	v_mov_b64_e32 v[14:15], s[68:69]
	v_max3_f32 v50, v34, v35, v18
	v_max3_f32 v51, v36, v37, v19
	s_nop 0
	v_max3_f32 v50, v50, v20, v21
	v_max3_f32 v51, v51, v40, v41
	s_nop 0
	v_max3_f32 v50, v50, v38, v39
	v_max3_f32 v51, v51, v24, v25
	s_nop 0
	v_max3_f32 v50, v50, v22, v23
	v_max3_f32 v51, v51, v44, v45
	s_nop 0
	v_max3_f32 v50, v50, v42, v43
	v_max3_f32 v51, v51, v28, v29
	s_nop 0
	v_max3_f32 v50, v50, v26, v27
	v_max3_f32 v51, v51, v48, v49
	s_nop 0
	v_max3_f32 v50, v50, v46, v47
	v_max3_f32 v51, v51, v32, v33
	s_nop 0
	v_max3_f32 v50, v50, v30, v31
	s_nop 0
	v_max_f32_e32 v50, v50, v51
	s_nop 0
	v_mov_b32_e32 v51, v50
	s_nop 1
	v_permlane32_swap_b32_e32 v50, v51
	v_max_f32_e32 v50, v50, v51
	s_nop 0
	v_sub_f32_e32 v66, v18, v50
	v_sub_f32_e32 v67, v19, v50
	v_mad_i64_i32 v[18:19], s[24:25], s9, v217, v[174:175]
	s_mov_b32 m0, s21
	s_nop 0
	global_load_lds_dwordx4 v[18:19], off
	v_mad_i64_i32 v[18:19], s[24:25], s7, v217, v[176:177]
	s_add_i32 s9, s21, 0x8000
	s_mov_b32 m0, s9
	s_nop 0
	global_load_lds_dwordx4 v[18:19], off
	ds_read_b128 v[158:161], v197 offset:8192
	ds_read_b128 v[154:157], v197 offset:8704
	ds_read_b128 v[150:153], v197 offset:10240
	ds_read_b128 v[146:149], v197 offset:10752
	ds_read_b128 v[142:145], v197 offset:12288
	ds_read_b128 v[138:141], v197 offset:12800
	ds_read_b128 v[134:137], v197 offset:14336
	ds_read_b128 v[130:133], v197 offset:14848
	v_sub_f32_e32 v34, v34, v50
	v_sub_f32_e32 v35, v35, v50
	v_sub_f32_e32 v36, v36, v50
	v_sub_f32_e32 v37, v37, v50
	v_sub_f32_e32 v38, v38, v50
	v_sub_f32_e32 v39, v39, v50
	v_sub_f32_e32 v40, v40, v50
	v_sub_f32_e32 v41, v41, v50
	v_sub_f32_e32 v42, v42, v50
	v_sub_f32_e32 v43, v43, v50
	v_sub_f32_e32 v44, v44, v50
	v_sub_f32_e32 v45, v45, v50
	v_sub_f32_e32 v46, v46, v50
	v_sub_f32_e32 v47, v47, v50
	v_sub_f32_e32 v48, v48, v50
	v_sub_f32_e32 v49, v49, v50
	v_add_f32_e32 v196, v1, v50
	v_sub_f32_e32 v20, v20, v50
	v_sub_f32_e32 v21, v21, v50
	v_sub_f32_e32 v22, v22, v50
	v_sub_f32_e32 v23, v23, v50
	v_sub_f32_e32 v24, v24, v50
	v_sub_f32_e32 v25, v25, v50
	v_sub_f32_e32 v26, v26, v50
	v_sub_f32_e32 v27, v27, v50
	v_sub_f32_e32 v28, v28, v50
	v_sub_f32_e32 v29, v29, v50
	v_sub_f32_e32 v30, v30, v50
	v_sub_f32_e32 v31, v31, v50
	v_sub_f32_e32 v32, v32, v50
	v_sub_f32_e32 v33, v33, v50
	s_nop 0
	v_exp_f32_e32 v65, v49
	v_exp_f32_e32 v50, v34
	v_exp_f32_e32 v51, v35
	v_exp_f32_e32 v52, v36
	v_exp_f32_e32 v53, v37
	v_exp_f32_e32 v54, v38
	v_exp_f32_e32 v55, v39
	v_exp_f32_e32 v56, v40
	v_exp_f32_e32 v57, v41
	v_exp_f32_e32 v58, v42
	v_exp_f32_e32 v59, v43
	v_exp_f32_e32 v60, v44
	v_exp_f32_e32 v61, v45
	v_exp_f32_e32 v62, v46
	v_exp_f32_e32 v63, v47
	v_exp_f32_e32 v64, v48
	v_exp_f32_e32 v49, v33
	v_exp_f32_e32 v34, v66
	v_exp_f32_e32 v35, v67
	v_exp_f32_e32 v36, v20
	v_exp_f32_e32 v37, v21
	v_exp_f32_e32 v38, v22
	v_exp_f32_e32 v39, v23
	v_exp_f32_e32 v40, v24
	v_exp_f32_e32 v41, v25
	v_exp_f32_e32 v42, v26
	v_exp_f32_e32 v43, v27
	v_exp_f32_e32 v44, v28
	v_exp_f32_e32 v45, v29
	v_exp_f32_e32 v46, v30
	v_exp_f32_e32 v47, v31
	v_exp_f32_e32 v48, v32
	s_add_i32 s24, s5, s4
	s_min_u32 s4, s4, 4
	s_waitcnt vmcnt(2) lgkmcnt(0)
	s_barrier
	v_med3_i32 v199, s24, 4, v218
	s_add_i32 s5, s5, s4
	s_lshl_b32 s1, s4, 6
	v_readfirstlane_b32 s9, v199
	s_mul_i32 s5, s5, 31
	s_sub_i32 s31, s0, s1
	s_bitset1_b32 s0, 7
	v_mov_b64_e32 v[32:33], v[16:17]
	s_add_i32 s25, s20, -5
	s_sub_i32 s26, s19, s9
	s_add_i32 s9, s10, 0xffffff40
	s_addk_i32 s10, 0xff80
	s_sub_i32 s11, 0xe5, s5
	s_sub_i32 s28, s0, s1
	s_sub_i32 s27, 0xc9, s5
	v_mov_b64_e32 v[30:31], v[14:15]
	v_mov_b64_e32 v[28:29], v[12:13]
	v_mov_b64_e32 v[26:27], v[10:11]
	v_mov_b64_e32 v[24:25], v[8:9]
	v_mov_b64_e32 v[22:23], v[6:7]
	v_mov_b64_e32 v[20:21], v[4:5]
	v_mov_b64_e32 v[18:19], v[2:3]
	.p2alignl 8, 3212836864
